# attention units dealt so that 8 neighbouring workgroups take the 8 heads of the same (group,batch,block) walk (G=256 only)
# speedup vs baseline: 1.0006x; 1.0006x over previous
; #define GAS __attribute__((address_space(1)))
; #define LAS __attribute__((address_space(3)))
; __device__ __forceinline__ void attn_prefetch(const AttnU& U, bool cont, const bf16* Kb, const bf16* Vb, const bf16* Qb, int tid, int wave, int lane, v4u (&pk)[6], v4u (&pv)[6], bf16x8 (&qn)[4]) {
;     const int r0 = cont ? 128 : 0, nch = cont ? 4 : 6;
; #pragma unroll
;     for (int i = 0; i < 6; ++i) { const int ci = tid + 512 * i, row = r0 + (ci >> 3), c8 = ci & 7, key = U.k0 + row;
;         if (i >= nch) { pk[i] = (v4u){0u, 0u, 0u, 0u}; pv[i] = pk[i]; }
;         else if (key >= 0) { const size_t o = (U.tokbase + (size_t)U.dil * key) * AW + U.colq + 8 * c8; pk[i] = *(const GAS v4u*)(Kb + o); pv[i] = *(const GAS v4u*)(Vb + o); }
;         else { pk[i] = (v4u){0u, 0u, 0u, 0u}; pv[i] = pk[i]; } }
;     const bf16* qrow = Qb + (U.tokbase + (size_t)U.dil * (U.k0 + 128 + 32 * wave + (lane & 31))) * AW + U.colq + 8 * (lane >> 5);
; #pragma unroll
;     for (int s = 0; s < 4; ++s) qn[s] = *(const GAS bf16x8*)(qrow + 16 * s);
; __device__ __forceinline__ void attn_prompt_phase(const Frame& F, const Args& A) {
;     ...
;     constexpr int NU = 3 * 8 * 8 * 32;
;     const int per = (NU + F.G - 1) / F.G, lo = blockIdx.x * per, hi = (lo + per < NU) ? lo + per : NU;
;     if (lo >= hi) return;
;     LAS unsigned char* AK = F.lds + L_AK; LAS unsigned char* AV = F.lds + L_AV;
;     v4u pk[6], pv[6]; bf16x8 qn[4];
;     AttnU U = attn_unit_decode(lo);
;     attn_prefetch(U, false, Kb, Vb, Qb, tid, w, lane, pk, pv, qn);
.LBB0_1136:
	s_or_b64 exec, exec, s[4:5]
	s_abs_i32 s0, s33
	v_cvt_f32_u32_e32 v1, s0
	s_sub_i32 s3, 0, s0
	s_add_i32 s1, s33, 0x17ff
	s_xor_b32 s2, s1, s33
	v_rcp_iflag_f32_e32 v1, v1
	s_abs_i32 s1, s1
	s_ashr_i32 s2, s2, 31
	v_writelane_b32 v254, s83, 32
	v_mul_f32_e32 v1, 0x4f7ffffe, v1
	v_cvt_u32_f32_e32 v1, v1
	v_mov_b32_e32 v57, v242
	v_mov_b32_e32 v56, v0
	s_mov_b32 s65, 0
	v_readfirstlane_b32 s4, v1
	s_mul_i32 s3, s3, s4
	s_mul_hi_u32 s3, s4, s3
	s_add_i32 s4, s4, s3
	s_mul_hi_u32 s3, s1, s4
	s_mul_i32 s4, s3, s0
	s_sub_i32 s1, s1, s4
	s_add_i32 s4, s3, 1
	s_sub_i32 s5, s1, s0
	s_cmp_ge_u32 s1, s0
	s_cselect_b32 s3, s4, s3
	s_cselect_b32 s1, s5, s1
	s_add_i32 s4, s3, 1
	s_cmp_ge_u32 s1, s0
	s_cselect_b32 s0, s4, s3
	s_xor_b32 s0, s0, s2
	s_sub_i32 s0, s0, s2
	s_mul_i32 s10, s0, s83
	s_add_i32 s0, s10, s0
	s_min_i32 s63, s0, 0x1800
	s_cmp_lg_u32 s33, 0x100
	s_cbranch_scc1 .Lattn_noremap
	s_lshr_b32 s10, s83, 3
	s_mul_i32 s10, s10, 24
	s_add_i32 s63, s10, 24
	s_and_b32 s100, s83, 7
	s_lshl_b32 s100, s100, 5
	s_lshr_b32 s101, s10, 5
	s_lshl_b32 s101, s101, 8
	s_and_b32 s10, s10, 31
	s_or_b32 s10, s10, s101
	s_or_b32 s10, s10, s100
	s_lshr_b32 s101, s63, 5
	s_lshl_b32 s101, s101, 8
	s_and_b32 s63, s63, 31
	s_or_b32 s63, s63, s101
	s_or_b32 s63, s63, s100
.Lattn_noremap:
	s_mov_b32 s0, s84
	s_cmp_ge_i32 s10, s63
	v_writelane_b32 v254, s0, 33
	s_mov_b32 s95, s59
	s_nop 0
	v_writelane_b32 v254, s1, 34
	s_cbranch_scc1 .LBB0_1219
	s_ashr_i32 s79, s10, 11
	s_mov_b64 s[0:1], 0x71200000
	s_lshl_b32 s4, s79, 1
	v_lshl_add_u64 v[134:135], v[50:51], 0, s[0:1]
	s_mov_b64 s[0:1], 0x7d300000
	s_lshr_b32 s2, 32, s4
	v_lshl_add_u64 v[136:137], v[50:51], 0, s[0:1]
	s_and_b32 s0, s10, 31
	s_sub_i32 s1, 5, s4
	s_add_i32 s2, s2, -1
	s_lshr_b32 s1, s0, s1
	s_and_b32 s0, s2, s0
	s_lshl_b32 s11, s10, 5
	s_bfe_u32 s42, s10, 0x30005
	s_and_b32 s2, s11, 0xe000
	s_lshl_b32 s0, s0, 8
	v_mov_b32_e32 v6, 0
	s_or_b32 s64, s1, s2
	s_addk_i32 s0, 0xff80
	s_lshl_b32 s1, s79, 9
	s_lshl_b32 s2, s42, 6
	v_lshlrev_b32_e32 v1, 3, v56
	v_ashrrev_i32_e32 v143, 3, v56
	v_mov_b32_e32 v8, v6
	v_mov_b32_e32 v9, v6
	s_or_b32 s6, s2, s1
	v_and_b32_e32 v1, 56, v1
	v_add_u32_e32 v10, s0, v143
	v_mov_b32_e32 v7, v6
	v_mov_b64_e32 v[128:129], v[8:9]
	v_cmp_lt_i32_e32 vcc, -1, v10
	v_or_b32_e32 v52, s6, v1
	v_mov_b64_e32 v[126:127], v[6:7]
	v_mov_b32_e32 v2, 0
	v_mov_b32_e32 v3, 0
	v_mov_b32_e32 v4, 0
	v_mov_b32_e32 v5, 0
	s_and_saveexec_b64 s[8:9], vcc
	s_cbranch_execz .LBB0_1139
	v_mov_b32_e32 v11, v6
	v_lshlrev_b64 v[2:3], s4, v[10:11]
	s_ashr_i32 s1, s6, 31
	v_lshl_add_u64 v[2:3], v[2:3], 0, s[64:65]
	v_mov_b32_e32 v53, s1
	s_movk_i32 s1, 0x600
	v_mad_u64_u32 v[4:5], s[2:3], v2, s1, v[52:53]
	v_mov_b32_e32 v2, v5
	v_mad_u64_u32 v[2:3], s[2:3], v3, s1, v[2:3]
	v_mov_b32_e32 v5, v2
	v_lshlrev_b64 v[2:3], 1, v[4:5]
	v_lshl_add_u64 v[4:5], v[134:135], 0, v[2:3]
	v_lshl_add_u64 v[8:9], v[136:137], 0, v[2:3]
	global_load_dwordx4 v[2:5], v[4:5], off
	s_nop 0
	global_load_dwordx4 v[126:129], v[8:9], off

; #define LAS __attribute__((address_space(3)))
; __device__ __forceinline__ void attn_prompt_phase(const Frame& F, const Args& A) {
;     ...
;     for (int u = lo; u < hi; ++u) {
;         __syncthreads();
;         rot = cont ? (rot + 8 >= 12 ? rot - 4 : rot + 8) : 0;
;         { const int r0 = cont ? 128 : 0, nch = cont ? 4 : 6;
; #pragma unroll
;           for (int i = 0; i < 6; ++i) if (i < nch) { const int ci = tid + 512 * i, rl = r0 + (ci >> 3), c8 = ci & 7; int sl = rot + (rl >> 5); sl = sl >= 12 ? sl - 12 : sl;
;               const int row = sl * 32 + (rl & 31); *(LAS v4u*)(AK + row * KS_ + 16 * c8) = pk[i]; *(LAS v4u*)(AV + row * KS_ + 16 * c8) = pv[i]; } }
;         bf16x8 qf[4];
; #pragma unroll
;         for (int s = 0; s < 4; ++s) qf[s] = qn[s];
;         const AttnU C = U;
;         if (u + 1 < hi) { U = attn_unit_decode(u + 1);
;             cont = (((u + 1) >> 5) == (u >> 5)) && (U.tokbase == C.tokbase) && (U.k0 == C.k0 + 256);
;             attn_prefetch(U, cont, Kb, Vb, Qb, tid, w, lane, pk, pv, qn); }
.LBB0_1163:
	s_add_i32 s82, s10, 1
	s_cmp_lg_u32 s33, 0x100
	s_cbranch_scc1 .Lattn_inc_done
	s_and_b32 s100, s10, 31
	s_cmp_eq_u32 s100, 31
	s_cselect_b32 s100, 225, 1
	s_add_i32 s82, s10, s100
.Lattn_inc_done:
	s_cmp_ge_i32 s82, s63
	s_cselect_b64 s[68:69], -1, 0
	v_mov_b64_e32 v[68:69], v[44:45]
	v_mov_b64_e32 v[120:121], v[40:41]
	v_mov_b64_e32 v[124:125], v[36:37]
	v_mov_b64_e32 v[132:133], v[8:9]
	s_and_b64 vcc, exec, s[68:69]
	s_mov_b64 s[60:61], s[64:65]
	s_mov_b32 s90, s43
	s_mov_b32 s86, s0
	s_mov_b32 s83, s79
	s_mov_b32 s87, s42
	v_mov_b64_e32 v[66:67], v[42:43]
	v_mov_b64_e32 v[118:119], v[38:39]
	v_mov_b64_e32 v[122:123], v[34:35]
	v_mov_b64_e32 v[130:131], v[6:7]
	s_cbranch_vccnz .LBB0_1197
	s_ashr_i32 s83, s82, 11
	s_lshl_b32 s14, s83, 1
	s_lshr_b32 s9, 32, s14
	s_and_b32 s4, s82, 31
	s_add_i32 s9, s9, -1
	s_sub_i32 s8, 5, s14
	s_and_b32 s9, s9, s4
	s_lshr_b32 s8, s4, s8
	s_lshl_b32 s62, s82, 5
	s_and_b32 s4, s62, 0xe000
	s_lshl_b32 s15, s9, 8
	s_or_b32 s4, s8, s4
	s_add_i32 s86, s15, 0xffffff80
	s_xor_b32 s8, s82, s10
	s_cmp_lt_u32 s8, 32
	s_cselect_b64 s[8:9], -1, 0
	s_cmp_eq_u64 s[64:65], s[4:5]
	s_cselect_b64 s[10:11], -1, 0
	s_add_i32 s12, s0, 0x180
	s_cmp_eq_u32 s15, s12
	s_cselect_b64 s[12:13], -1, 0
	s_and_b64 s[10:11], s[10:11], s[12:13]
	s_and_b64 s[66:67], s[10:11], s[8:9]
	s_and_b64 s[8:9], s[66:67], exec
	s_cselect_b32 s15, s15, s86
	v_add_u32_e32 v2, s15, v143
	v_cmp_gt_i32_e32 vcc, 0, v2
	s_and_saveexec_b64 s[8:9], vcc
	s_xor_b64 s[8:9], exec, s[8:9]
	s_or_saveexec_b64 s[10:11], s[8:9]
	s_bfe_u32 s87, s82, 0x30005
	v_mov_b32_e32 v72, v70
	v_mov_b32_e32 v73, v70
	s_lshl_b32 s8, s83, 9
	s_lshl_b32 s9, s87, 6
	v_mov_b32_e32 v71, v70
	v_mov_b64_e32 v[128:129], v[72:73]
	s_or_b32 s8, s9, s8
	v_mov_b32_e32 v74, 0
	v_mov_b64_e32 v[126:127], v[70:71]
	v_mov_b32_e32 v75, 0
	v_mov_b32_e32 v76, 0
	v_mov_b32_e32 v77, 0
	s_xor_b64 exec, exec, s[10:11]
	s_cbranch_execz .LBB0_1168
	v_mov_b32_e32 v3, v70
	v_lshlrev_b64 v[2:3], s14, v[2:3]
	s_ashr_i32 s9, s8, 31
	v_lshl_add_u64 v[2:3], v[2:3], 0, s[4:5]
	v_mov_b32_e32 v5, s9
	v_or_b32_e32 v4, s8, v1
	v_mad_u64_u32 v[4:5], s[12:13], v2, s72, v[4:5]
	v_mov_b32_e32 v2, v5
	v_mad_u64_u32 v[2:3], s[12:13], v3, s72, v[2:3]
	v_mov_b32_e32 v5, v2
	v_lshlrev_b64 v[2:3], 1, v[4:5]
	v_lshl_add_u64 v[4:5], v[134:135], 0, v[2:3]
	v_lshl_add_u64 v[2:3], v[136:137], 0, v[2:3]
	global_load_dwordx4 v[74:77], v[4:5], off
	global_load_dwordx4 v[126:129], v[2:3], off
